# attention P.V chains read V fragments with two ds_read_b64 instead of one ds_read2_b64 (DA and MLA loops)
# speedup vs baseline: 1.0026x; 1.0026x over previous
; #define LAS __attribute__((address_space(3)))
; #define MFMA32(a, b, c) __builtin_amdgcn_mfma_f32_32x32x16_bf16((a), (b), (c), 0, 0, 0)
; template <int MODE>
; DI void attn_unit(LAS unsigned char* lds, const bf16_t* Qg, int ldq, const bf16_t* Kg, int ldk, const bf16_t* VTg, int ldvt, bf16_t* Og, int ldo,
;                   int q0, int NT, const float* gout, const float* relb, float lam, float osc, const float* qgain) {
;     ...
;     auto pvdo = [&](const int vbi, const u32x4 (&pp)[4]) {
;         const LAS unsigned char* Vb = lds + VB0 + vbi * VBSZ + (r32 + (MODE == 2 ? mm * 64 : 0)) * VSTR + hi * 8;
; #pragma unroll
;         for (int d = 0; d < NDB; ++d)
; #pragma unroll
;             for (int ks = 0; ks < 4; ++ks) { const int kb = 32 * (ks >> 1) + 16 * (ks & 1);
;                 const s16x4 lo = *(const LAS s16x4*)(Vb + d * 32 * VSTR + kb * 2), hh = *(const LAS s16x4*)(Vb + d * 32 * VSTR + kb * 2 + 16);
;                 const bf16x8 vf = __builtin_shufflevector(lo, hh, 0, 1, 2, 3, 4, 5, 6, 7);
;                 o[d] = MFMA32(vf, __builtin_bit_cast(bf16x8, pp[ks]), o[d]); }
;     };
;     ...
;         if (skew && t >= 1 && (t - 1) < ntw) pvdo(vprev, pk);
.LBB0_188:
	s_add_i32 s2, s15, -1
	s_cmp_le_u32 s2, s18
	s_cselect_b64 s[10:11], -1, 0
	s_and_b64 s[10:11], s[0:1], s[10:11]
	s_andn2_b64 vcc, exec, s[10:11]
	s_cbranch_vccnz .LBB0_190
	s_mul_i32 s3, s13, 0x4400
	s_addk_i32 s3, 0xbc00
	s_cmp_lg_u32 s13, 0
	s_cselect_b32 s3, s3, 0x8800
	v_add_u32_e32 v0, s3, v67
	v_add_u32_e32 v236, 0x8800, v0
	v_add_u32_e32 v237, 0x9800, v0
	v_add_u32_e32 v238, 0xa800, v0
	v_add_u32_e32 v239, 0xb800, v0
	ds_read_b64 v[212:213], v236
	ds_read_b64 v[214:215], v236 offset:16
	ds_read_b64 v[216:217], v236 offset:32
	ds_read_b64 v[218:219], v236 offset:48
	ds_read_b64 v[220:221], v236 offset:64
	ds_read_b64 v[222:223], v236 offset:80
	ds_read_b64 v[224:225], v236 offset:96
	ds_read_b64 v[226:227], v236 offset:112
	s_waitcnt lgkmcnt(4)
	v_mfma_f32_32x32x16_bf16 v[50:65], v[212:215], v[96:99], v[50:65]
	v_mfma_f32_32x32x16_bf16 v[50:65], v[216:219], v[92:95], v[50:65]
	ds_read_b64 v[212:213], v237 offset:256
	ds_read_b64 v[214:215], v237 offset:272
	ds_read_b64 v[216:217], v237 offset:288
	ds_read_b64 v[218:219], v237 offset:304
	s_waitcnt lgkmcnt(4)
	v_mfma_f32_32x32x16_bf16 v[50:65], v[220:223], v[88:91], v[50:65]
	v_mfma_f32_32x32x16_bf16 v[50:65], v[224:227], v[84:87], v[50:65]
	ds_read_b64 v[220:221], v237 offset:320
	ds_read_b64 v[222:223], v237 offset:336
	ds_read_b64 v[224:225], v237 offset:352
	ds_read_b64 v[226:227], v237 offset:368
	s_waitcnt lgkmcnt(4)
	v_mfma_f32_32x32x16_bf16 v[34:49], v[212:215], v[96:99], v[34:49]
	v_mfma_f32_32x32x16_bf16 v[34:49], v[216:219], v[92:95], v[34:49]
	ds_read_b64 v[212:213], v238 offset:512
	ds_read_b64 v[214:215], v238 offset:528
	ds_read_b64 v[216:217], v238 offset:544
	ds_read_b64 v[218:219], v238 offset:560
	s_waitcnt lgkmcnt(4)
	v_mfma_f32_32x32x16_bf16 v[34:49], v[220:223], v[88:91], v[34:49]
	v_mfma_f32_32x32x16_bf16 v[34:49], v[224:227], v[84:87], v[34:49]
	ds_read_b64 v[220:221], v238 offset:576
	ds_read_b64 v[222:223], v238 offset:592
	ds_read_b64 v[224:225], v238 offset:608
	ds_read_b64 v[226:227], v238 offset:624
	s_waitcnt lgkmcnt(4)
	v_mfma_f32_32x32x16_bf16 v[18:33], v[212:215], v[96:99], v[18:33]
	v_mfma_f32_32x32x16_bf16 v[18:33], v[216:219], v[92:95], v[18:33]
	ds_read_b64 v[212:213], v239 offset:768
	ds_read_b64 v[214:215], v239 offset:784
	ds_read_b64 v[216:217], v239 offset:800
	ds_read_b64 v[218:219], v239 offset:816
	s_waitcnt lgkmcnt(4)
	v_mfma_f32_32x32x16_bf16 v[18:33], v[220:223], v[88:91], v[18:33]
	v_mfma_f32_32x32x16_bf16 v[18:33], v[224:227], v[84:87], v[18:33]
	ds_read_b64 v[220:221], v239 offset:832
	ds_read_b64 v[222:223], v239 offset:848
	ds_read_b64 v[224:225], v239 offset:864
	ds_read_b64 v[226:227], v239 offset:880
	s_waitcnt lgkmcnt(4)
	v_mfma_f32_32x32x16_bf16 v[2:17], v[212:215], v[96:99], v[2:17]
	v_mfma_f32_32x32x16_bf16 v[2:17], v[216:219], v[92:95], v[2:17]
	s_waitcnt lgkmcnt(0)
	v_mfma_f32_32x32x16_bf16 v[2:17], v[220:223], v[88:91], v[2:17]
	v_mfma_f32_32x32x16_bf16 v[2:17], v[224:227], v[84:87], v[2:17]

; #define LAS __attribute__((address_space(3)))
; template <int MODE>
; DI void attn_unit(LAS unsigned char* lds, const bf16_t* Qg, int ldq, const bf16_t* Kg, int ldk, const bf16_t* VTg, int ldvt, bf16_t* Og, int ldo,
;                   int q0, int NT, const float* gout, const float* relb, float lam, float osc, const float* qgain) {
;     ...
;     auto pvdo = [&](const int vbi, const u32x4 (&pp)[4]) {
;         const LAS unsigned char* Vb = lds + VB0 + vbi * VBSZ + (r32 + (MODE == 2 ? mm * 64 : 0)) * VSTR + hi * 8;
; #pragma unroll
;         for (int d = 0; d < NDB; ++d)
; #pragma unroll
;             for (int ks = 0; ks < 4; ++ks) { const int kb = 32 * (ks >> 1) + 16 * (ks & 1);
;     ...
;                 float rs = 0.f;
; #pragma unroll
;                 for (int i = 0; i < 16; ++i) { p0[i] = ex2(p0[i]); p1[i] = ex2(p1[i]); rs += p0[i] + p1[i]; }
;                 lrun += rs;
;             } else {
;                 f32x16 L0, L1;
;                 const bool diag = (NT - 1 - t) == TD;
;                 sb_prep(p0, L0, key0 + 4 * hi, qrow, diag); sb_prep(p1, L1, key0 + 32 + 4 * hi, qrow, diag);
;                 float own[8], par[8];
; #pragma unroll
;                 for (int g = 0; g < 4; ++g) { own[g] = (L0[4 * g] + L0[4 * g + 1]) + (L0[4 * g + 2] + L0[4 * g + 3]); own[4 + g] = (L1[4 * g] + L1[4 * g + 1]) + (L1[4 * g + 2] + L1[4 * g + 3]); }
; #pragma unroll
;                 for (int g = 0; g < 8; ++g) par[g] = shx(own[g], 32, lane);
;                 float so = 0.f, sp2 = 0.f;
; #pragma unroll
;                 for (int g = 7; g >= 0; --g) {
;                     const float SG = R + so + sp2 + (hi == 0 ? par[g] : 0.f);
;                     float w = 0.f;
; #pragma unroll
;                     for (int e = 3; e >= 0; --e) { const int idx = 4 * (g & 3) + e;
;                         if (g >= 4) { p1[idx] = ex2(p1[idx] + SG + w); w += L1[idx]; } else { p0[idx] = ex2(p0[idx] + SG + w); w += L0[idx]; } }
;                     so += own[g]; sp2 += par[g];
;                 }
;                 R += so + sp2;
;             }
; #pragma unroll
;             for (int j = 0; j < 4; ++j) { pk[0][j] = cvtpk(p0[2 * j], p0[2 * j + 1]); pk[1][j] = cvtpk(p0[8 + 2 * j], p0[8 + 2 * j + 1]);
;                 pk[2][j] = cvtpk(p1[2 * j], p1[2 * j + 1]); pk[3][j] = cvtpk(p1[8 + 2 * j], p1[8 + 2 * j + 1]); }
;             if (!skew) pvdo(vcur, pk);
.LBB0_195:
	v_exp_f32_e32 v179, v84
	v_exp_f32_e32 v196, v100
	v_exp_f32_e32 v0, v85
	v_exp_f32_e32 v178, v101
	v_exp_f32_e32 v175, v86
	v_exp_f32_e32 v177, v102
	v_exp_f32_e32 v174, v87
	v_exp_f32_e32 v176, v103
	v_exp_f32_e32 v171, v88
	v_exp_f32_e32 v173, v104
	v_exp_f32_e32 v170, v89
	v_exp_f32_e32 v172, v105
	v_exp_f32_e32 v167, v90
	v_exp_f32_e32 v169, v106
	v_exp_f32_e32 v166, v91
	v_exp_f32_e32 v168, v107
	v_exp_f32_e32 v163, v92
	v_exp_f32_e32 v165, v108
	v_exp_f32_e32 v162, v93
	v_exp_f32_e32 v164, v109
	v_exp_f32_e32 v109, v94
	v_exp_f32_e32 v195, v110
	v_exp_f32_e32 v108, v95
	v_exp_f32_e32 v110, v111
	v_exp_f32_e32 v105, v96
	v_exp_f32_e32 v107, v112
	v_exp_f32_e32 v104, v97
	v_exp_f32_e32 v106, v113
	v_exp_f32_e32 v101, v98
	v_exp_f32_e32 v103, v114
	v_exp_f32_e32 v100, v99
	v_exp_f32_e32 v102, v115
	v_cvt_pk_bf16_f32 v96, v179, v0
	v_cvt_pk_bf16_f32 v92, v163, v162
	v_cvt_pk_bf16_f32 v88, v196, v178
	v_cvt_pk_bf16_f32 v84, v165, v164
	v_cvt_pk_bf16_f32 v97, v175, v174
	v_cvt_pk_bf16_f32 v93, v109, v108
	v_cvt_pk_bf16_f32 v89, v177, v176
	v_cvt_pk_bf16_f32 v85, v195, v110
	v_cvt_pk_bf16_f32 v98, v171, v170
	v_cvt_pk_bf16_f32 v94, v105, v104
	v_cvt_pk_bf16_f32 v90, v173, v172
	v_cvt_pk_bf16_f32 v86, v107, v106
	v_cvt_pk_bf16_f32 v99, v167, v166
	v_cvt_pk_bf16_f32 v95, v101, v100
	v_cvt_pk_bf16_f32 v91, v169, v168
	s_andn2_b64 vcc, exec, s[6:7]
	v_cvt_pk_bf16_f32 v87, v103, v102
	s_cbranch_vccnz .LBB0_197
	s_mul_i32 s2, s13, 0x4400
	v_add_u32_e32 v240, s2, v67
	v_add_u32_e32 v236, 0x8800, v240
	v_add_u32_e32 v237, 0x9800, v240
	v_add_u32_e32 v238, 0xa800, v240
	v_add_u32_e32 v239, 0xb800, v240
	ds_read_b64 v[212:213], v236
	ds_read_b64 v[214:215], v236 offset:16
	ds_read_b64 v[216:217], v236 offset:32
	ds_read_b64 v[218:219], v236 offset:48
	ds_read_b64 v[220:221], v236 offset:64
	ds_read_b64 v[222:223], v236 offset:80
	ds_read_b64 v[224:225], v236 offset:96
	ds_read_b64 v[226:227], v236 offset:112
	s_waitcnt lgkmcnt(4)
	v_mfma_f32_32x32x16_bf16 v[50:65], v[212:215], v[96:99], v[50:65]
	v_mfma_f32_32x32x16_bf16 v[50:65], v[216:219], v[92:95], v[50:65]
	ds_read_b64 v[212:213], v237 offset:256
	ds_read_b64 v[214:215], v237 offset:272
	ds_read_b64 v[216:217], v237 offset:288
	ds_read_b64 v[218:219], v237 offset:304
	s_waitcnt lgkmcnt(4)
	v_mfma_f32_32x32x16_bf16 v[50:65], v[220:223], v[88:91], v[50:65]
	v_mfma_f32_32x32x16_bf16 v[50:65], v[224:227], v[84:87], v[50:65]
	ds_read_b64 v[220:221], v237 offset:320
	ds_read_b64 v[222:223], v237 offset:336
	ds_read_b64 v[224:225], v237 offset:352
	ds_read_b64 v[226:227], v237 offset:368
	s_waitcnt lgkmcnt(4)
	v_mfma_f32_32x32x16_bf16 v[34:49], v[212:215], v[96:99], v[34:49]
	v_mfma_f32_32x32x16_bf16 v[34:49], v[216:219], v[92:95], v[34:49]
	ds_read_b64 v[212:213], v238 offset:512
	ds_read_b64 v[214:215], v238 offset:528
	ds_read_b64 v[216:217], v238 offset:544
	ds_read_b64 v[218:219], v238 offset:560
	s_waitcnt lgkmcnt(4)
	v_mfma_f32_32x32x16_bf16 v[34:49], v[220:223], v[88:91], v[34:49]
	v_mfma_f32_32x32x16_bf16 v[34:49], v[224:227], v[84:87], v[34:49]
	ds_read_b64 v[220:221], v238 offset:576
	ds_read_b64 v[222:223], v238 offset:592
	ds_read_b64 v[224:225], v238 offset:608
	ds_read_b64 v[226:227], v238 offset:624
	s_waitcnt lgkmcnt(4)
	v_mfma_f32_32x32x16_bf16 v[18:33], v[212:215], v[96:99], v[18:33]
	v_mfma_f32_32x32x16_bf16 v[18:33], v[216:219], v[92:95], v[18:33]
	ds_read_b64 v[212:213], v239 offset:768
	ds_read_b64 v[214:215], v239 offset:784
	ds_read_b64 v[216:217], v239 offset:800
	ds_read_b64 v[218:219], v239 offset:816
	s_waitcnt lgkmcnt(4)
	v_mfma_f32_32x32x16_bf16 v[18:33], v[220:223], v[88:91], v[18:33]
	v_mfma_f32_32x32x16_bf16 v[18:33], v[224:227], v[84:87], v[18:33]
	ds_read_b64 v[220:221], v239 offset:832
	ds_read_b64 v[222:223], v239 offset:848
	ds_read_b64 v[224:225], v239 offset:864
	ds_read_b64 v[226:227], v239 offset:880
	s_waitcnt lgkmcnt(4)
	v_mfma_f32_32x32x16_bf16 v[2:17], v[212:215], v[96:99], v[2:17]
	v_mfma_f32_32x32x16_bf16 v[2:17], v[216:219], v[92:95], v[2:17]
	s_waitcnt lgkmcnt(0)
	v_mfma_f32_32x32x16_bf16 v[2:17], v[220:223], v[88:91], v[2:17]
	v_mfma_f32_32x32x16_bf16 v[2:17], v[224:227], v[84:87], v[2:17]

; #define LAS __attribute__((address_space(3)))
; #define MFMA32(a, b, c) __builtin_amdgcn_mfma_f32_32x32x16_bf16((a), (b), (c), 0, 0, 0)
; template <int MODE>
; DI void attn_unit(LAS unsigned char* lds, const bf16_t* Qg, int ldq, const bf16_t* Kg, int ldk, const bf16_t* VTg, int ldvt, bf16_t* Og, int ldo,
;                   int q0, int NT, const float* gout, const float* relb, float lam, float osc, const float* qgain) {
;     ...
;     auto pvdo = [&](const int vbi, const u32x4 (&pp)[4]) {
;         const LAS unsigned char* Vb = lds + VB0 + vbi * VBSZ + (r32 + (MODE == 2 ? mm * 64 : 0)) * VSTR + hi * 8;
; #pragma unroll
;         for (int d = 0; d < NDB; ++d)
; #pragma unroll
;             for (int ks = 0; ks < 4; ++ks) { const int kb = 32 * (ks >> 1) + 16 * (ks & 1);
;                 const s16x4 lo = *(const LAS s16x4*)(Vb + d * 32 * VSTR + kb * 2), hh = *(const LAS s16x4*)(Vb + d * 32 * VSTR + kb * 2 + 16);
;                 const bf16x8 vf = __builtin_shufflevector(lo, hh, 0, 1, 2, 3, 4, 5, 6, 7);
;                 o[d] = MFMA32(vf, __builtin_bit_cast(bf16x8, pp[ks]), o[d]); }
;     };
;     ...
;         if (t + 1 < NT) AT_GLOAD(AT_KEY0(t + 1));
;         const int key0 = AT_KEY0(t);
;         bool active;
;         if (MODE == 2) active = (NT - 1 - t) <= TD; else active = t < ntw;
;         bool alive = true;
;         if (MODE == 2) alive = !active || __any(R > -150.f);
;         if (skew && t >= 1 && (t - 1) < ntw) pvdo(vprev, pk);
.LBB0_238:
	s_or_b64 exec, exec, s[6:7]
	global_load_dwordx4 v[2:5], v[142:143], off
	s_add_i32 s2, s13, 3
	s_cmp_le_i32 s2, s10
	s_cselect_b64 s[6:7], -1, 0
	s_and_b64 s[6:7], s[0:1], s[6:7]
	s_andn2_b64 vcc, exec, s[6:7]
	s_cbranch_vccnz .LBB0_240
	s_mul_i32 s3, s11, 0x4400
	s_addk_i32 s3, 0xbc00
	s_cmp_lg_u32 s11, 0
	s_cselect_b32 s3, s3, 0x8800
	v_add_u32_e32 v0, s3, v163
	v_add_u32_e32 v236, 0x8800, v0
	v_add_u32_e32 v237, 0x9800, v0
	ds_read_b64 v[212:213], v236
	ds_read_b64 v[214:215], v236 offset:16
	ds_read_b64 v[216:217], v236 offset:32
	ds_read_b64 v[218:219], v236 offset:48
	ds_read_b64 v[220:221], v236 offset:64
	ds_read_b64 v[222:223], v236 offset:80
	ds_read_b64 v[224:225], v236 offset:96
	ds_read_b64 v[226:227], v236 offset:112
	s_waitcnt lgkmcnt(4)
	v_mfma_f32_32x32x16_bf16 v[32:47], v[212:215], v[68:71], v[32:47]
	v_mfma_f32_32x32x16_bf16 v[32:47], v[216:219], v[64:67], v[32:47]
	ds_read_b64 v[212:213], v237 offset:256
	ds_read_b64 v[214:215], v237 offset:272
	ds_read_b64 v[216:217], v237 offset:288
	ds_read_b64 v[218:219], v237 offset:304
	s_waitcnt lgkmcnt(4)
	v_mfma_f32_32x32x16_bf16 v[32:47], v[220:223], v[10:13], v[32:47]
	v_mfma_f32_32x32x16_bf16 v[32:47], v[224:227], v[6:9], v[32:47]
	ds_read_b64 v[220:221], v237 offset:320
	ds_read_b64 v[222:223], v237 offset:336
	ds_read_b64 v[224:225], v237 offset:352
	ds_read_b64 v[226:227], v237 offset:368
	s_waitcnt lgkmcnt(4)
	v_mfma_f32_32x32x16_bf16 v[16:31], v[212:215], v[68:71], v[16:31]
	v_mfma_f32_32x32x16_bf16 v[16:31], v[216:219], v[64:67], v[16:31]
	s_waitcnt lgkmcnt(0)
	v_mfma_f32_32x32x16_bf16 v[16:31], v[220:223], v[10:13], v[16:31]
	v_mfma_f32_32x32x16_bf16 v[16:31], v[224:227], v[6:9], v[16:31]

; #define LAS __attribute__((address_space(3)))
; template <int MODE>
; DI void attn_unit(LAS unsigned char* lds, const bf16_t* Qg, int ldq, const bf16_t* Kg, int ldk, const bf16_t* VTg, int ldvt, bf16_t* Og, int ldo,
;                   int q0, int NT, const float* gout, const float* relb, float lam, float osc, const float* qgain) {
;     ...
;     auto pvdo = [&](const int vbi, const u32x4 (&pp)[4]) {
;         const LAS unsigned char* Vb = lds + VB0 + vbi * VBSZ + (r32 + (MODE == 2 ? mm * 64 : 0)) * VSTR + hi * 8;
; #pragma unroll
;         for (int d = 0; d < NDB; ++d)
; #pragma unroll
;             for (int ks = 0; ks < 4; ++ks) { const int kb = 32 * (ks >> 1) + 16 * (ks & 1);
;     ...
;                 float rs = 0.f;
; #pragma unroll
;                 for (int i = 0; i < 16; ++i) { p0[i] = ex2(p0[i]); p1[i] = ex2(p1[i]); rs += p0[i] + p1[i]; }
;                 lrun += rs;
;             } else {
;                 f32x16 L0, L1;
;                 const bool diag = (NT - 1 - t) == TD;
;                 sb_prep(p0, L0, key0 + 4 * hi, qrow, diag); sb_prep(p1, L1, key0 + 32 + 4 * hi, qrow, diag);
;                 float own[8], par[8];
; #pragma unroll
;                 for (int g = 0; g < 4; ++g) { own[g] = (L0[4 * g] + L0[4 * g + 1]) + (L0[4 * g + 2] + L0[4 * g + 3]); own[4 + g] = (L1[4 * g] + L1[4 * g + 1]) + (L1[4 * g + 2] + L1[4 * g + 3]); }
; #pragma unroll
;                 for (int g = 0; g < 8; ++g) par[g] = shx(own[g], 32, lane);
;                 float so = 0.f, sp2 = 0.f;
; #pragma unroll
;                 for (int g = 7; g >= 0; --g) {
;                     const float SG = R + so + sp2 + (hi == 0 ? par[g] : 0.f);
;                     float w = 0.f;
; #pragma unroll
;                     for (int e = 3; e >= 0; --e) { const int idx = 4 * (g & 3) + e;
;                         if (g >= 4) { p1[idx] = ex2(p1[idx] + SG + w); w += L1[idx]; } else { p0[idx] = ex2(p0[idx] + SG + w); w += L0[idx]; } }
;                     so += own[g]; sp2 += par[g];
;                 }
;                 R += so + sp2;
;             }
; #pragma unroll
;             for (int j = 0; j < 4; ++j) { pk[0][j] = cvtpk(p0[2 * j], p0[2 * j + 1]); pk[1][j] = cvtpk(p0[8 + 2 * j], p0[8 + 2 * j + 1]);
;                 pk[2][j] = cvtpk(p1[2 * j], p1[2 * j + 1]); pk[3][j] = cvtpk(p1[8 + 2 * j], p1[8 + 2 * j + 1]); }
;             if (!skew) pvdo(vcur, pk);
.LBB0_243:
	v_exp_f32_e32 v159, v80
	v_exp_f32_e32 v173, v64
	v_exp_f32_e32 v158, v81
	v_exp_f32_e32 v0, v65
	v_exp_f32_e32 v155, v82
	v_exp_f32_e32 v157, v66
	v_exp_f32_e32 v154, v83
	v_exp_f32_e32 v156, v67
	v_exp_f32_e32 v151, v84
	v_exp_f32_e32 v153, v68
	v_exp_f32_e32 v150, v85
	v_exp_f32_e32 v152, v69
	v_exp_f32_e32 v145, v86
	v_exp_f32_e32 v147, v70
	v_exp_f32_e32 v144, v87
	v_exp_f32_e32 v146, v71
	v_exp_f32_e32 v87, v88
	v_exp_f32_e32 v172, v72
	v_exp_f32_e32 v86, v89
	v_exp_f32_e32 v88, v73
	v_exp_f32_e32 v83, v90
	v_exp_f32_e32 v85, v74
	v_exp_f32_e32 v82, v91
	v_exp_f32_e32 v84, v75
	v_exp_f32_e32 v81, v92
	v_exp_f32_e32 v90, v76
	v_exp_f32_e32 v76, v93
	v_exp_f32_e32 v80, v77
	v_exp_f32_e32 v73, v94
	v_exp_f32_e32 v75, v78
	v_exp_f32_e32 v72, v95
	v_exp_f32_e32 v74, v79
	v_cvt_pk_bf16_f32 v68, v159, v158
	v_cvt_pk_bf16_f32 v64, v87, v86
	v_cvt_pk_bf16_f32 v10, v173, v0
	v_cvt_pk_bf16_f32 v6, v172, v88
	v_cvt_pk_bf16_f32 v69, v155, v154
	v_cvt_pk_bf16_f32 v65, v83, v82
	v_cvt_pk_bf16_f32 v11, v157, v156
	v_cvt_pk_bf16_f32 v7, v85, v84
	v_cvt_pk_bf16_f32 v70, v151, v150
	v_cvt_pk_bf16_f32 v66, v81, v76
	v_cvt_pk_bf16_f32 v12, v153, v152
	v_cvt_pk_bf16_f32 v8, v90, v80
	v_cvt_pk_bf16_f32 v71, v145, v144
	v_cvt_pk_bf16_f32 v67, v73, v72
	v_cvt_pk_bf16_f32 v13, v147, v146
	s_and_b64 vcc, exec, s[42:43]
	v_cvt_pk_bf16_f32 v9, v75, v74
	s_cbranch_vccnz .LBB0_245
	s_mul_i32 s2, s11, 0x4400
	v_add_u32_e32 v240, s2, v163
	v_add_u32_e32 v236, 0x8800, v240
	v_add_u32_e32 v237, 0x9800, v240
	ds_read_b64 v[212:213], v236
	ds_read_b64 v[214:215], v236 offset:16
	ds_read_b64 v[216:217], v236 offset:32
	ds_read_b64 v[218:219], v236 offset:48
	ds_read_b64 v[220:221], v236 offset:64
	ds_read_b64 v[222:223], v236 offset:80
	ds_read_b64 v[224:225], v236 offset:96
	ds_read_b64 v[226:227], v236 offset:112
	s_waitcnt lgkmcnt(4)
	v_mfma_f32_32x32x16_bf16 v[32:47], v[212:215], v[68:71], v[32:47]
	v_mfma_f32_32x32x16_bf16 v[32:47], v[216:219], v[64:67], v[32:47]
	ds_read_b64 v[212:213], v237 offset:256
	ds_read_b64 v[214:215], v237 offset:272
	ds_read_b64 v[216:217], v237 offset:288
	ds_read_b64 v[218:219], v237 offset:304
	s_waitcnt lgkmcnt(4)
	v_mfma_f32_32x32x16_bf16 v[32:47], v[220:223], v[10:13], v[32:47]
	v_mfma_f32_32x32x16_bf16 v[32:47], v[224:227], v[6:9], v[32:47]
	ds_read_b64 v[220:221], v237 offset:320
	ds_read_b64 v[222:223], v237 offset:336
	ds_read_b64 v[224:225], v237 offset:352
	ds_read_b64 v[226:227], v237 offset:368
	s_waitcnt lgkmcnt(4)
	v_mfma_f32_32x32x16_bf16 v[16:31], v[212:215], v[68:71], v[16:31]
	v_mfma_f32_32x32x16_bf16 v[16:31], v[216:219], v[64:67], v[16:31]
	s_waitcnt lgkmcnt(0)
	v_mfma_f32_32x32x16_bf16 v[16:31], v[220:223], v[10:13], v[16:31]
	v_mfma_f32_32x32x16_bf16 v[16:31], v[224:227], v[6:9], v[16:31]
